# on top of v36: nt hint on the 16 F1 epilogue gate loads per unit (PM tiles are read exactly once)
# baseline (speedup 1.0000x reference)
.Lf1e_201:
	s_lshl_b32 s22, s7, 11
	s_ashr_i32 s23, s22, 31
	s_cmp_lg_u32 s7, 0
	s_cselect_b64 s[24:25], -1, 0
	s_lshl_b32 s17, s6, 8
	s_lshl_b64 s[22:23], s[22:23], 1
	v_add_u32_e32 v210, s17, v217
	s_add_u32 s22, s39, s22
	v_ashrrev_i32_e32 v211, 31, v210
	s_addc_u32 s23, s40, s23
	v_lshl_or_b32 v208, s49, 8, v222
	v_lshlrev_b64 v[64:65], 14, v[210:211]
	v_lshl_add_u64 v[64:65], s[22:23], 0, v[64:65]
	v_ashrrev_i32_e32 v209, 31, v208
	v_lshl_add_u64 v[64:65], v[208:209], 1, v[64:65]
	global_load_dwordx4 v[188:191], v[64:65], off nt
	v_lshlrev_b64 v[66:67], 12, v[210:211]
	v_lshl_add_u64 v[66:67], s[10:11], 0, v[66:67]
	s_cmp_eq_u32 s7, 0
	v_lshl_add_u64 v[212:213], v[208:209], 1, v[66:67]
	s_cbranch_scc1 .LBB0_882
.LBB0_882:
	global_load_dwordx4 v[184:187], v[64:65], off offset:256 nt
	v_cndmask_b32_e64 v64, 0, 1, s[24:25]
	v_cmp_ne_u32_e64 s[6:7], 1, v64
	s_andn2_b64 vcc, exec, s[24:25]
	s_cbranch_vccnz .LBB0_884
.LBB0_884:
	v_or_b32_e32 v64, 16, v210
	v_ashrrev_i32_e32 v65, 31, v64
	v_lshlrev_b64 v[66:67], 14, v[64:65]
	v_lshl_add_u64 v[66:67], s[22:23], 0, v[66:67]
	v_lshl_add_u64 v[66:67], v[208:209], 1, v[66:67]
	global_load_dwordx4 v[180:183], v[66:67], off nt
	v_lshlrev_b64 v[64:65], 12, v[64:65]
	v_lshl_add_u64 v[64:65], s[10:11], 0, v[64:65]
	s_and_b64 vcc, exec, s[6:7]
	v_lshl_add_u64 v[64:65], v[208:209], 1, v[64:65]
	s_cbranch_vccnz .LBB0_886
.LBB0_886:
	global_load_dwordx4 v[176:179], v[66:67], off offset:256 nt
	s_and_b64 vcc, exec, s[6:7]
	s_cbranch_vccnz .LBB0_888
.LBB0_888:
	v_or_b32_e32 v64, 32, v210
	v_ashrrev_i32_e32 v65, 31, v64
	v_lshlrev_b64 v[66:67], 14, v[64:65]
	v_lshl_add_u64 v[66:67], s[22:23], 0, v[66:67]
	v_lshl_add_u64 v[66:67], v[208:209], 1, v[66:67]
	global_load_dwordx4 v[172:175], v[66:67], off nt
	v_lshlrev_b64 v[64:65], 12, v[64:65]
	v_lshl_add_u64 v[64:65], s[10:11], 0, v[64:65]
	s_and_b64 vcc, exec, s[6:7]
	v_lshl_add_u64 v[64:65], v[208:209], 1, v[64:65]
	s_cbranch_vccnz .LBB0_890
.LBB0_890:
	global_load_dwordx4 v[168:171], v[66:67], off offset:256 nt
	s_and_b64 vcc, exec, s[6:7]
	s_cbranch_vccnz .LBB0_892
.LBB0_892:
	v_or_b32_e32 v66, 48, v210
	v_ashrrev_i32_e32 v67, 31, v66
	v_lshlrev_b64 v[64:65], 14, v[66:67]
	v_lshl_add_u64 v[64:65], s[22:23], 0, v[64:65]
	v_lshl_add_u64 v[64:65], v[208:209], 1, v[64:65]
	global_load_dwordx4 v[164:167], v[64:65], off nt
	v_lshlrev_b64 v[66:67], 12, v[66:67]
	v_lshl_add_u64 v[66:67], s[10:11], 0, v[66:67]
	s_and_b64 vcc, exec, s[6:7]
	v_lshl_add_u64 v[214:215], v[208:209], 1, v[66:67]
	s_cbranch_vccnz .LBB0_894
	ds_read_b128 v[68:71], v252
.LBB0_894:
	global_load_dwordx4 v[160:163], v[64:65], off offset:256 nt
	s_and_b64 vcc, exec, s[6:7]
	s_cbranch_vccnz .LBB0_896
	ds_read_b128 v[64:67], v252 offset:8192

.Lf1k_103:
	v_add_u32_e32 v72, 0x80, v210
	v_ashrrev_i32_e32 v73, 31, v72
	v_lshlrev_b64 v[74:75], 14, v[72:73]
	v_lshl_add_u64 v[74:75], s[22:23], 0, v[74:75]
	v_lshl_add_u64 v[74:75], v[208:209], 1, v[74:75]
	global_load_dwordx4 v[116:119], v[74:75], off nt
	v_lshlrev_b64 v[76:77], 12, v[72:73]
	v_lshl_add_u64 v[76:77], s[10:11], 0, v[76:77]
	s_and_b64 vcc, exec, s[6:7]
	v_lshl_add_u64 v[124:125], v[208:209], 1, v[76:77]
	s_cbranch_vccnz .LBB0_914
.LBB0_914:
	global_load_dwordx4 v[112:115], v[74:75], off offset:256 nt
	s_and_b64 vcc, exec, s[6:7]
	s_cbranch_vccnz .LBB0_916
.LBB0_916:
	v_or_b32_e32 v74, 16, v72
	v_ashrrev_i32_e32 v75, 31, v74
	v_lshlrev_b64 v[76:77], 14, v[74:75]
	v_lshl_add_u64 v[76:77], s[22:23], 0, v[76:77]
	v_lshl_add_u64 v[76:77], v[208:209], 1, v[76:77]
	global_load_dwordx4 v[104:107], v[76:77], off nt
	v_lshlrev_b64 v[74:75], 12, v[74:75]
	v_lshl_add_u64 v[74:75], s[10:11], 0, v[74:75]
	s_and_b64 vcc, exec, s[6:7]
	v_lshl_add_u64 v[74:75], v[208:209], 1, v[74:75]
	s_cbranch_vccnz .LBB0_918
.LBB0_918:
	global_load_dwordx4 v[96:99], v[76:77], off offset:256 nt
	s_and_b64 vcc, exec, s[6:7]
	s_cbranch_vccnz .LBB0_920
.LBB0_920:
	v_or_b32_e32 v74, 32, v72
	v_ashrrev_i32_e32 v75, 31, v74
	v_lshlrev_b64 v[76:77], 14, v[74:75]
	v_lshl_add_u64 v[76:77], s[22:23], 0, v[76:77]
	v_lshl_add_u64 v[76:77], v[208:209], 1, v[76:77]
	global_load_dwordx4 v[92:95], v[76:77], off nt
	v_lshlrev_b64 v[74:75], 12, v[74:75]
	v_lshl_add_u64 v[74:75], s[10:11], 0, v[74:75]
	s_and_b64 vcc, exec, s[6:7]
	v_lshl_add_u64 v[74:75], v[208:209], 1, v[74:75]
	s_cbranch_vccnz .LBB0_922
.LBB0_922:
	global_load_dwordx4 v[84:87], v[76:77], off offset:256 nt
	s_and_b64 vcc, exec, s[6:7]
	s_cbranch_vccnz .LBB0_924
.LBB0_924:
	v_or_b32_e32 v74, 48, v72
	v_ashrrev_i32_e32 v75, 31, v74
	v_lshlrev_b64 v[72:73], 14, v[74:75]
	v_lshl_add_u64 v[72:73], s[22:23], 0, v[72:73]
	v_lshl_add_u64 v[72:73], v[208:209], 1, v[72:73]
	global_load_dwordx4 v[76:79], v[72:73], off nt
	v_lshlrev_b64 v[74:75], 12, v[74:75]
	v_lshl_add_u64 v[74:75], s[10:11], 0, v[74:75]
	s_and_b64 vcc, exec, s[6:7]
	v_lshl_add_u64 v[126:127], v[208:209], 1, v[74:75]
	s_cbranch_vccnz .LBB0_926
	global_load_dwordx4 v[68:71], v[126:127], off
.LBB0_926:
	s_nop 0
	global_load_dwordx4 v[72:75], v[72:73], off offset:256 nt
	s_and_b64 vcc, exec, s[6:7]
	s_cbranch_vccnz .LBB0_928
	global_load_dwordx4 v[64:67], v[126:127], off offset:256
